# v009 + QKV phases (P1,P3) un-ALIGNed: leading half starts its epilogue during the trailing half's last MFMA block; ALIGN barrier kept only before the last unit
# baseline (speedup 1.0000x reference)
; #define PG8_STAGE(bufoff, gbase, voff) do { _Pragma("unroll") for (int _i = 0; _i < 2; ++_i) \
;         __builtin_amdgcn_global_load_lds((const unsigned*)((const char*)(gbase) + (voff)[_i]), (PG8_LAS unsigned*)(lds + (bufoff) + ldsw + _i * 8192), 16, 0, PG8_LOAD_AUX); } while (0)
; #define PG8_LDA(dst, b, h) do { _Pragma("unroll") for (int m = 0; m < 4; ++m) _Pragma("unroll") for (int k = 0; k < 2; ++k) dst[m][k] = *(const PG8_LAS bf16x8*)(lds + PG8_SA(b, h) + aoff + m * 2048 + k * 1024); } while (0)
; #define PG8_LDB(dst, b, h) do { _Pragma("unroll") for (int n = 0; n < 2; ++n) _Pragma("unroll") for (int k = 0; k < 2; ++k) dst[n][k] = *(const PG8_LAS bf16x8*)(lds + PG8_SB(b, h) + boff + n * 2048 + k * 1024); } while (0)
; #define PG8_MMA(ai, bj, At, Bt) do { __builtin_amdgcn_s_setprio(1); _Pragma("unroll") for (int m = 0; m < 4; ++m) _Pragma("unroll") for (int n = 0; n < 2; ++n) _Pragma("unroll") for (int k = 0; k < 2; ++k) \
;         acc[ai][bj][m][n] = __builtin_amdgcn_mfma_f32_16x16x32_bf16(Bt[n][k], At[m][k], acc[ai][bj][m][n], 0, 0, 0); __builtin_amdgcn_s_setprio(0); } while (0)
; #define PG8_WAIT_V(n) asm volatile("s_waitcnt vmcnt(" #n ")" ::: "memory")
; #define PG8_WAIT_L(n) asm volatile("s_waitcnt lgkmcnt(" #n ")" ::: "memory")
; #define PG8_BAR __builtin_amdgcn_s_barrier()
; #define PG8_SCHED __builtin_amdgcn_sched_barrier(0)
; template <class Epi, class Sched, bool ALIGN_EPI = false, bool SP2 = false>
; __device__ __forceinline__ void gemm_phase(PG8_LAS unsigned char* lds, const Gemm g, const Sched& S, const Epi& E) {
;     ...
;             PG8_LDB(B0, 1, 0); PG8_LDB(B1, 1, 1); PG8_SCHED; PG8_LDA(At, 1, 0); PG8_STAGE(PG8_SA(0, 1), a2 + hstepA, voffA);
;             PG8_WAIT_V(8); PG8_WAIT_L(0); PG8_BAR; PG8_MMA(0, 0, At, B0); PG8_MMA(0, 1, At, B1); PG8_BAR; PG8_SCHED;
;             PG8_LDA(At, 1, 1); PG8_STAGE(PG8_SB(1, 0), b3, voffB); PG8_STAGE(PG8_SB(1, 1), b3 + hstepB, voffB); PG8_STAGE(PG8_SA(1, 0), a3, voffA);
;             PG8_WAIT_V(8); PG8_WAIT_L(0); PG8_BAR; PG8_MMA(1, 0, At, B0); PG8_MMA(1, 1, At, B1); PG8_BAR; PG8_SCHED;
.Lkmid_P1:
	s_add_i32 s29, 0, 0x18000
	v_add_u32_e32 v161, s29, v146
	s_add_i32 s38, 0, 0x1c000
	ds_read_b128 v[162:165], v161
	ds_read_b128 v[166:169], v161 offset:1024
	ds_read_b128 v[170:173], v161 offset:2048
	ds_read_b128 v[174:177], v161 offset:3072
	v_add_u32_e32 v161, s38, v146
	ds_read_b128 v[178:181], v161
	ds_read_b128 v[182:185], v161 offset:1024
	ds_read_b128 v[186:189], v161 offset:2048
	ds_read_b128 v[190:193], v161 offset:3072
	s_add_u32 s30, s34, 0x40000
	s_addc_u32 s31, s35, 0
	s_mov_b32 m0, s44
	v_lshl_add_u64 v[234:235], s[30:31], 0, v[128:129]
	ds_read_b128 v[194:197], v160 offset:32768
	ds_read_b128 v[198:201], v160 offset:33792
	ds_read_b128 v[202:205], v160 offset:34816
	ds_read_b128 v[206:209], v160 offset:35840
	ds_read_b128 v[210:213], v160 offset:36864
	ds_read_b128 v[214:217], v160 offset:37888
	ds_read_b128 v[218:221], v160 offset:38912
	ds_read_b128 v[222:225], v160 offset:39936
	global_load_lds_dwordx4 v[234:235], off
	v_lshl_add_u64 v[234:235], s[30:31], 0, v[132:133]
	s_mov_b32 m0, s45
	s_nop 0
	global_load_lds_dwordx4 v[234:235], off
	s_waitcnt vmcnt(8)
	s_waitcnt lgkmcnt(0)
	s_barrier
	s_waitcnt lgkmcnt(0)
	v_mfma_f32_16x16x32_bf16 v[124:127], v[162:165], v[194:197], v[124:127]
	v_mfma_f32_16x16x32_bf16 v[120:123], v[170:173], v[194:197], v[120:123]
	v_mfma_f32_16x16x32_bf16 v[108:111], v[162:165], v[202:205], v[108:111]
	v_mfma_f32_16x16x32_bf16 v[104:107], v[170:173], v[202:205], v[104:107]
	v_mfma_f32_16x16x32_bf16 v[92:95], v[162:165], v[210:213], v[92:95]
	v_mfma_f32_16x16x32_bf16 v[88:91], v[170:173], v[210:213], v[88:91]
	v_mfma_f32_16x16x32_bf16 v[76:79], v[162:165], v[218:221], v[76:79]
	v_mfma_f32_16x16x32_bf16 v[72:75], v[170:173], v[218:221], v[72:75]
	v_mfma_f32_16x16x32_bf16 v[124:127], v[166:169], v[198:201], v[124:127]
	v_mfma_f32_16x16x32_bf16 v[120:123], v[174:177], v[198:201], v[120:123]
	v_mfma_f32_16x16x32_bf16 v[108:111], v[166:169], v[206:209], v[108:111]
	v_mfma_f32_16x16x32_bf16 v[104:107], v[174:177], v[206:209], v[104:107]
	v_mfma_f32_16x16x32_bf16 v[92:95], v[166:169], v[214:217], v[92:95]
	v_mfma_f32_16x16x32_bf16 v[88:91], v[174:177], v[214:217], v[88:91]
	v_mfma_f32_16x16x32_bf16 v[76:79], v[166:169], v[222:225], v[76:79]
	v_mfma_f32_16x16x32_bf16 v[72:75], v[174:177], v[222:225], v[72:75]
	v_mfma_f32_16x16x32_bf16 v[116:119], v[178:181], v[194:197], v[116:119]
	v_mfma_f32_16x16x32_bf16 v[112:115], v[186:189], v[194:197], v[112:115]
	v_mfma_f32_16x16x32_bf16 v[100:103], v[178:181], v[202:205], v[100:103]
	v_mfma_f32_16x16x32_bf16 v[96:99], v[186:189], v[202:205], v[96:99]
	v_mfma_f32_16x16x32_bf16 v[84:87], v[178:181], v[210:213], v[84:87]
	v_mfma_f32_16x16x32_bf16 v[80:83], v[186:189], v[210:213], v[80:83]
	v_mfma_f32_16x16x32_bf16 v[68:71], v[178:181], v[218:221], v[68:71]
	v_mfma_f32_16x16x32_bf16 v[64:67], v[186:189], v[218:221], v[64:67]
	v_mfma_f32_16x16x32_bf16 v[116:119], v[182:185], v[198:201], v[116:119]
	v_mfma_f32_16x16x32_bf16 v[112:115], v[190:193], v[198:201], v[112:115]
	v_mfma_f32_16x16x32_bf16 v[100:103], v[182:185], v[206:209], v[100:103]
	v_mfma_f32_16x16x32_bf16 v[96:99], v[190:193], v[206:209], v[96:99]
	v_mfma_f32_16x16x32_bf16 v[84:87], v[182:185], v[214:217], v[84:87]
	v_mfma_f32_16x16x32_bf16 v[80:83], v[190:193], v[214:217], v[80:83]
	v_mfma_f32_16x16x32_bf16 v[68:71], v[182:185], v[222:225], v[68:71]
	v_mfma_f32_16x16x32_bf16 v[64:67], v[190:193], v[222:225], v[64:67]
	s_barrier
	s_add_i32 s29, s29, s33
	v_lshl_add_u64 v[226:227], v[226:227], 0, s[10:11]
	s_mov_b32 m0, s29
	ds_read_b128 v[194:197], v160 offset:49152
	ds_read_b128 v[198:201], v160 offset:50176
	ds_read_b128 v[202:205], v160 offset:51200
	ds_read_b128 v[206:209], v160 offset:52224
	ds_read_b128 v[210:213], v160 offset:53248
	ds_read_b128 v[214:217], v160 offset:54272
	ds_read_b128 v[218:221], v160 offset:55296
	ds_read_b128 v[222:225], v160 offset:56320
	global_load_lds_dwordx4 v[226:227], off
	s_add_i32 m0, s29, 0x2000
	s_add_u32 s22, s22, 0x10080
	v_lshl_add_u64 v[226:227], v[228:229], 0, s[10:11]
	s_addc_u32 s23, s23, 0
	s_add_i32 s29, s38, s33
	global_load_lds_dwordx4 v[226:227], off
	v_lshl_add_u64 v[226:227], s[22:23], 0, v[130:131]
	s_mov_b32 m0, s29
	s_nop 0
	global_load_lds_dwordx4 v[226:227], off
	v_lshl_add_u64 v[226:227], s[22:23], 0, v[134:135]
	s_add_i32 m0, s29, 0x2000
	s_nop 0
	global_load_lds_dwordx4 v[226:227], off
	v_lshl_add_u64 v[226:227], v[230:231], 0, s[10:11]
	s_mov_b32 m0, s48
	s_nop 0
	global_load_lds_dwordx4 v[226:227], off
	v_lshl_add_u64 v[226:227], v[232:233], 0, s[10:11]
	s_mov_b32 m0, s49
	s_nop 0
	global_load_lds_dwordx4 v[226:227], off
	s_waitcnt vmcnt(8)
	s_waitcnt lgkmcnt(0)
	s_barrier
; __device__ __forceinline__ unsigned cvt_pk_bf16(float lo, float hi) { const cvt_f32x2_t v = {lo, hi}; const cvt_bf16x2_t b = __builtin_convertvector(v, cvt_bf16x2_t); return __builtin_bit_cast(unsigned, b); }
; #define PG8_STAGE(bufoff, gbase, voff) do { _Pragma("unroll") for (int _i = 0; _i < 2; ++_i) \
;         __builtin_amdgcn_global_load_lds((const unsigned*)((const char*)(gbase) + (voff)[_i]), (PG8_LAS unsigned*)(lds + (bufoff) + ldsw + _i * 8192), 16, 0, PG8_LOAD_AUX); } while (0)
; #define PG8_LDA(dst, b, h) do { _Pragma("unroll") for (int m = 0; m < 4; ++m) _Pragma("unroll") for (int k = 0; k < 2; ++k) dst[m][k] = *(const PG8_LAS bf16x8*)(lds + PG8_SA(b, h) + aoff + m * 2048 + k * 1024); } while (0)
; #define PG8_WAIT_V(n) asm volatile("s_waitcnt vmcnt(" #n ")" ::: "memory")
; #define PG8_WAIT_L(n) asm volatile("s_waitcnt lgkmcnt(" #n ")" ::: "memory")
; #define PG8_BAR __builtin_amdgcn_s_barrier()
;     __device__ __forceinline__ void operator()(const f32x4 (&acc)[2][2][4][2], const Unit& u, int wr, int wc, int fr, int fq) const {
;         const int col0 = u.pn * BM + wc * 64 + 8 * fq;
; #pragma unroll
;         for (int ai = 0; ai < 2; ++ai)
; #pragma unroll
;             for (int m = 0; m < 4; ++m) { const int rowg = u.pm * BM + ai * HALF + wr * 64 + m * 16;
;                 const float sc = slots ? rstd_from_slots(slots, rowg + fr, fq) : 1.0f;
;                 u32x4 w[2];
; #pragma unroll
;                 for (int bj = 0; bj < 2; ++bj) { const f32x4 v0 = acc[ai][bj][m][0] * sc, v1 = acc[ai][bj][m][1] * sc;
;                     w[bj].x = cvt_pk_bf16(v0[0], v0[1]); w[bj].y = cvt_pk_bf16(v0[2], v0[3]); w[bj].z = cvt_pk_bf16(v1[0], v1[1]); w[bj].w = cvt_pk_bf16(v1[2], v1[3]); }
;                 wide_store(O, ldc, rowg, col0, fr, w[0], w[1]); }
; template <class Epi, class Sched, bool ALIGN_EPI = false, bool SP2 = false>
; __device__ __forceinline__ void gemm_phase(PG8_LAS unsigned char* lds, const Gemm g, const Sched& S, const Epi& E) {
;     ...
;             PG8_WAIT_V(8); PG8_WAIT_L(0); PG8_BAR; PG8_MMA(0, 0, At, B0); PG8_MMA(0, 1, At, B1); PG8_BAR; PG8_SCHED;
;             PG8_LDA(At, 1, 1); PG8_STAGE(PG8_SB(1, 0), b3, voffB); PG8_STAGE(PG8_SB(1, 1), b3 + hstepB, voffB); PG8_STAGE(PG8_SA(1, 0), a3, voffA);
;             PG8_WAIT_V(8); PG8_WAIT_L(0); PG8_BAR; PG8_MMA(1, 0, At, B0); PG8_MMA(1, 1, At, B1); PG8_BAR; PG8_SCHED;
	s_waitcnt lgkmcnt(0)
	v_mfma_f32_16x16x32_bf16 v[60:63], v[162:165], v[194:197], v[60:63]
	v_mfma_f32_16x16x32_bf16 v[56:59], v[170:173], v[194:197], v[56:59]
	v_mfma_f32_16x16x32_bf16 v[44:47], v[162:165], v[202:205], v[44:47]
	v_mfma_f32_16x16x32_bf16 v[40:43], v[170:173], v[202:205], v[40:43]
	v_mfma_f32_16x16x32_bf16 v[28:31], v[162:165], v[210:213], v[28:31]
	v_mfma_f32_16x16x32_bf16 v[24:27], v[170:173], v[210:213], v[24:27]
	v_mfma_f32_16x16x32_bf16 v[12:15], v[162:165], v[218:221], v[12:15]
	v_mfma_f32_16x16x32_bf16 v[8:11], v[170:173], v[218:221], v[8:11]
	v_mfma_f32_16x16x32_bf16 v[60:63], v[166:169], v[198:201], v[60:63]
	v_mfma_f32_16x16x32_bf16 v[56:59], v[174:177], v[198:201], v[56:59]
	v_mfma_f32_16x16x32_bf16 v[44:47], v[166:169], v[206:209], v[44:47]
	v_mfma_f32_16x16x32_bf16 v[40:43], v[174:177], v[206:209], v[40:43]
	v_mfma_f32_16x16x32_bf16 v[28:31], v[166:169], v[214:217], v[28:31]
	v_mfma_f32_16x16x32_bf16 v[24:27], v[174:177], v[214:217], v[24:27]
	v_mfma_f32_16x16x32_bf16 v[12:15], v[166:169], v[222:225], v[12:15]
	v_mfma_f32_16x16x32_bf16 v[8:11], v[174:177], v[222:225], v[8:11]
	v_mfma_f32_16x16x32_bf16 v[52:55], v[178:181], v[194:197], v[52:55]
	v_mfma_f32_16x16x32_bf16 v[48:51], v[186:189], v[194:197], v[48:51]
	v_mfma_f32_16x16x32_bf16 v[36:39], v[178:181], v[202:205], v[36:39]
	v_mfma_f32_16x16x32_bf16 v[32:35], v[186:189], v[202:205], v[32:35]
	v_mfma_f32_16x16x32_bf16 v[20:23], v[178:181], v[210:213], v[20:23]
	v_mfma_f32_16x16x32_bf16 v[16:19], v[186:189], v[210:213], v[16:19]
	v_mfma_f32_16x16x32_bf16 v[4:7], v[178:181], v[218:221], v[4:7]
	v_mfma_f32_16x16x32_bf16 v[0:3], v[186:189], v[218:221], v[0:3]
	v_mfma_f32_16x16x32_bf16 v[52:55], v[182:185], v[198:201], v[52:55]
	v_mfma_f32_16x16x32_bf16 v[48:51], v[190:193], v[198:201], v[48:51]
	v_mfma_f32_16x16x32_bf16 v[36:39], v[182:185], v[206:209], v[36:39]
	v_mfma_f32_16x16x32_bf16 v[32:35], v[190:193], v[206:209], v[32:35]
	v_mfma_f32_16x16x32_bf16 v[20:23], v[182:185], v[214:217], v[20:23]
	v_mfma_f32_16x16x32_bf16 v[16:19], v[190:193], v[214:217], v[16:19]
	v_mfma_f32_16x16x32_bf16 v[4:7], v[182:185], v[222:225], v[4:7]
	v_mfma_f32_16x16x32_bf16 v[0:3], v[190:193], v[222:225], v[0:3]
	s_barrier
	s_add_i32 s28, s28, 2
	s_add_u32 s20, s20, 0x100
	s_addc_u32 s21, s21, 0
	s_add_u32 s26, s26, 0x100
	s_addc_u32 s27, s27, 0
	s_cmp_gt_u32 s28, 13
	s_cbranch_scc0 .LBB0_215
	s_andn2_b64 vcc, s[12:13], s[4:5]
	s_cbranch_vccz .LBB0_218
	s_barrier
.LBB0_218:
	v_cvt_pk_bf16_f32 v120, v120, v121
	v_cvt_pk_bf16_f32 v112, v112, v113
	v_cvt_pk_bf16_f32 v121, v122, v123
	v_cvt_pk_bf16_f32 v113, v114, v115
	v_cndmask_b32_e64 v115, v120, v112, s[2:3]
	v_mov_b32_e32 v122, 0
	v_cvt_pk_bf16_f32 v124, v124, v125
	v_cvt_pk_bf16_f32 v125, v126, v127
	v_cvt_pk_bf16_f32 v126, v116, v117
	v_cvt_pk_bf16_f32 v127, v118, v119
	v_cndmask_b32_e64 v114, v121, v113, s[2:3]
	v_mov_b32_dpp v122, v115 row_ror:8 row_mask:0xf bank_mask:0xf
	v_mov_b32_e32 v115, 0
	v_readlane_b32 s30, v239, 49
	v_lshl_or_b32 v162, s1, 8, v147
	s_lshl_b32 s0, s0, 8
	v_cndmask_b32_e64 v116, v125, v127, s[2:3]
	v_cndmask_b32_e64 v117, v124, v126, s[2:3]
	v_mov_b32_e32 v161, 0
	v_mov_b32_e32 v164, 0
	v_mov_b32_dpp v115, v114 row_ror:8 row_mask:0xf bank_mask:0xf
	v_readlane_b32 s31, v239, 50
	v_cvt_pk_bf16_f32 v104, v104, v105
	v_cvt_pk_bf16_f32 v100, v100, v101
	v_cvt_pk_bf16_f32 v101, v102, v103
	v_cvt_pk_bf16_f32 v102, v96, v97
	v_ashrrev_i32_e32 v163, 31, v162
	v_mov_b32_dpp v161, v117 row_ror:8 row_mask:0xf bank_mask:0xf
	v_mov_b32_dpp v164, v116 row_ror:8 row_mask:0xf bank_mask:0xf
	v_cndmask_b32_e64 v118, v122, v120, s[2:3]
	v_cndmask_b32_e64 v123, v113, v115, s[2:3]
	v_cndmask_b32_e64 v122, v112, v122, s[2:3]
	v_add_u32_e32 v114, s0, v148
	v_mov_b64_e32 v[112:113], s[30:31]
	v_cvt_pk_bf16_f32 v108, v108, v109
	v_cvt_pk_bf16_f32 v109, v110, v111
	v_cvt_pk_bf16_f32 v105, v106, v107
	v_cvt_pk_bf16_f32 v103, v98, v99
	v_cndmask_b32_e64 v97, v104, v102, s[2:3]
	v_mov_b32_e32 v110, v137
	v_cndmask_b32_e64 v119, v115, v121, s[2:3]
	v_cndmask_b32_e64 v117, v164, v125, s[2:3]
	v_cndmask_b32_e64 v116, v161, v124, s[2:3]
	v_mad_i64_i32 v[124:125], s[20:21], v114, s53, v[112:113]
	v_lshlrev_b64 v[114:115], 1, v[162:163]
	v_cndmask_b32_e64 v96, v105, v103, s[2:3]
	v_cndmask_b32_e64 v98, v109, v101, s[2:3]
	v_mov_b32_e32 v107, v137
	v_mov_b32_dpp v110, v97 row_ror:8 row_mask:0xf bank_mask:0xf
	v_mov_b32_e32 v111, v137
	v_cvt_pk_bf16_f32 v88, v88, v89
	v_cvt_pk_bf16_f32 v84, v84, v85
	v_cvt_pk_bf16_f32 v85, v86, v87
	v_cvt_pk_bf16_f32 v86, v80, v81
	v_lshl_add_u64 v[124:125], v[124:125], 0, v[114:115]
	v_cndmask_b32_e64 v99, v108, v100, s[2:3]
	v_mov_b32_e32 v106, v137
	v_mov_b32_dpp v107, v98 row_ror:8 row_mask:0xf bank_mask:0xf
	v_mov_b32_dpp v111, v96 row_ror:8 row_mask:0xf bank_mask:0xf
	v_cndmask_b32_e64 v98, v110, v104, s[2:3]
	v_add_u32_e32 v104, s0, v149
	v_cvt_pk_bf16_f32 v92, v92, v93
	v_cvt_pk_bf16_f32 v93, v94, v95
	v_cvt_pk_bf16_f32 v89, v90, v91
	v_cvt_pk_bf16_f32 v87, v82, v83
	v_cndmask_b32_e64 v81, v88, v86, s[2:3]
	v_mov_b32_e32 v94, v137
	v_lshl_add_u64 v[124:125], v[124:125], 0, v[136:137]
	v_mov_b32_dpp v106, v99 row_ror:8 row_mask:0xf bank_mask:0xf
	v_cndmask_b32_e64 v99, v111, v105, s[2:3]
	v_mad_i64_i32 v[104:105], s[20:21], v104, s53, v[112:113]
	v_cndmask_b32_e64 v80, v89, v87, s[2:3]
	v_cndmask_b32_e64 v82, v93, v85, s[2:3]
	v_mov_b32_e32 v91, v137
	v_mov_b32_dpp v94, v81 row_ror:8 row_mask:0xf bank_mask:0xf
	v_mov_b32_e32 v95, v137
	v_cvt_pk_bf16_f32 v72, v72, v73
	v_cvt_pk_bf16_f32 v68, v68, v69
	v_cvt_pk_bf16_f32 v69, v70, v71
	v_cvt_pk_bf16_f32 v70, v64, v65
	global_store_dwordx4 v[124:125], v[116:119], off nt
; __device__ __forceinline__ unsigned cvt_pk_bf16(float lo, float hi) { const cvt_f32x2_t v = {lo, hi}; const cvt_bf16x2_t b = __builtin_convertvector(v, cvt_bf16x2_t); return __builtin_bit_cast(unsigned, b); }
; __device__ __forceinline__ unsigned swap8(unsigned v) { return (unsigned)__builtin_amdgcn_update_dpp(0, (int)v, 0x128  , 0xF, 0xF, false); }
; __device__ __forceinline__ void wide_store(bf16_t* O, int ldc, int rowg  , int col0  , int fr, u32x4 w0, u32x4 w1) {
;     const bool lo = fr < 8;
;     u32x4 snd = lo ? w1 : w0, rcv;
;     rcv.x = swap8(snd.x); rcv.y = swap8(snd.y); rcv.z = swap8(snd.z); rcv.w = swap8(snd.w);
;     const u32x4 first = lo ? w0 : rcv, second = lo ? rcv : w1;
;     bf16_t* p = O + (size_t)(rowg + (fr & 7)) * ldc + col0 + (lo ? 0 : 32);
;     __builtin_nontemporal_store(first, (u32x4*)p); __builtin_nontemporal_store(second, (u32x4*)(p + (size_t)8 * ldc));
; }
;     __device__ __forceinline__ void operator()(const f32x4 (&acc)[2][2][4][2], const Unit& u, int wr, int wc, int fr, int fq) const {
;         const int col0 = u.pn * BM + wc * 64 + 8 * fq;
; #pragma unroll
;         for (int ai = 0; ai < 2; ++ai)
; #pragma unroll
;             for (int m = 0; m < 4; ++m) { const int rowg = u.pm * BM + ai * HALF + wr * 64 + m * 16;
;                 const float sc = slots ? rstd_from_slots(slots, rowg + fr, fq) : 1.0f;
;                 u32x4 w[2];
; #pragma unroll
;                 for (int bj = 0; bj < 2; ++bj) { const f32x4 v0 = acc[ai][bj][m][0] * sc, v1 = acc[ai][bj][m][1] * sc;
;                     w[bj].x = cvt_pk_bf16(v0[0], v0[1]); w[bj].y = cvt_pk_bf16(v0[2], v0[3]); w[bj].z = cvt_pk_bf16(v1[0], v1[1]); w[bj].w = cvt_pk_bf16(v1[2], v1[3]); }
;                 wide_store(O, ldc, rowg, col0, fr, w[0], w[1]); }
	v_lshl_add_u64 v[104:105], v[104:105], 0, v[114:115]
	v_cndmask_b32_e64 v83, v92, v84, s[2:3]
	v_add_co_u32_e32 v116, vcc, s54, v124
	v_mov_b32_e32 v90, v137
	v_mov_b32_dpp v91, v82 row_ror:8 row_mask:0xf bank_mask:0xf
	v_mov_b32_dpp v95, v80 row_ror:8 row_mask:0xf bank_mask:0xf
	v_cndmask_b32_e64 v82, v94, v88, s[2:3]
	v_add_u32_e32 v88, s0, v150
	v_cvt_pk_bf16_f32 v76, v76, v77
	v_cvt_pk_bf16_f32 v77, v78, v79
	v_cvt_pk_bf16_f32 v73, v74, v75
	v_cvt_pk_bf16_f32 v71, v66, v67
	v_cndmask_b32_e64 v65, v72, v70, s[2:3]
	v_mov_b32_e32 v78, v137
	v_cndmask_b32_e64 v121, v127, v164, s[2:3]
	v_cndmask_b32_e64 v120, v126, v161, s[2:3]
	v_addc_co_u32_e32 v117, vcc, 0, v125, vcc
	v_cndmask_b32_e64 v97, v107, v109, s[2:3]
	v_cndmask_b32_e64 v96, v106, v108, s[2:3]
	v_lshl_add_u64 v[104:105], v[104:105], 0, v[136:137]
	v_mov_b32_dpp v90, v83 row_ror:8 row_mask:0xf bank_mask:0xf
	v_cndmask_b32_e64 v83, v95, v89, s[2:3]
	v_mad_i64_i32 v[88:89], s[20:21], v88, s53, v[112:113]
	v_cndmask_b32_e64 v64, v73, v71, s[2:3]
	v_cndmask_b32_e64 v66, v77, v69, s[2:3]
	v_mov_b32_e32 v75, v137
	v_mov_b32_dpp v78, v65 row_ror:8 row_mask:0xf bank_mask:0xf
	v_mov_b32_e32 v79, v137
	v_cvt_pk_bf16_f32 v56, v56, v57
	v_cvt_pk_bf16_f32 v52, v52, v53
	v_cvt_pk_bf16_f32 v53, v54, v55
	v_cvt_pk_bf16_f32 v54, v48, v49
	global_store_dwordx4 v[116:117], v[120:123], off nt
	global_store_dwordx4 v[104:105], v[96:99], off nt
	v_lshl_add_u64 v[88:89], v[88:89], 0, v[114:115]
	v_cndmask_b32_e64 v67, v76, v68, s[2:3]
	v_add_co_u32_e32 v96, vcc, s54, v104
	v_mov_b32_e32 v74, v137
	v_mov_b32_dpp v75, v66 row_ror:8 row_mask:0xf bank_mask:0xf
	v_mov_b32_dpp v79, v64 row_ror:8 row_mask:0xf bank_mask:0xf
	v_cndmask_b32_e64 v66, v78, v72, s[2:3]
	v_add_u32_e32 v72, s0, v151
	v_cvt_pk_bf16_f32 v60, v60, v61
	v_cvt_pk_bf16_f32 v61, v62, v63
	v_cvt_pk_bf16_f32 v57, v58, v59
	v_cvt_pk_bf16_f32 v55, v50, v51
	v_cndmask_b32_e64 v49, v56, v54, s[2:3]
	v_mov_b32_e32 v62, v137
	v_cndmask_b32_e64 v103, v103, v111, s[2:3]
	v_cndmask_b32_e64 v102, v102, v110, s[2:3]
	v_cndmask_b32_e64 v101, v101, v107, s[2:3]
	v_cndmask_b32_e64 v100, v100, v106, s[2:3]
	v_addc_co_u32_e32 v97, vcc, 0, v105, vcc
	v_cndmask_b32_e64 v81, v91, v93, s[2:3]
	v_cndmask_b32_e64 v80, v90, v92, s[2:3]
	v_lshl_add_u64 v[88:89], v[88:89], 0, v[136:137]
	v_mov_b32_dpp v74, v67 row_ror:8 row_mask:0xf bank_mask:0xf
	v_cndmask_b32_e64 v67, v79, v73, s[2:3]
	v_mad_i64_i32 v[72:73], s[20:21], v72, s53, v[112:113]
	v_cndmask_b32_e64 v48, v57, v55, s[2:3]
	v_cndmask_b32_e64 v50, v61, v53, s[2:3]
	v_mov_b32_e32 v59, v137
	v_mov_b32_dpp v62, v49 row_ror:8 row_mask:0xf bank_mask:0xf
	v_mov_b32_e32 v63, v137
	v_cvt_pk_bf16_f32 v40, v40, v41
	v_cvt_pk_bf16_f32 v36, v36, v37
	v_cvt_pk_bf16_f32 v37, v38, v39
	v_cvt_pk_bf16_f32 v38, v32, v33
	global_store_dwordx4 v[96:97], v[100:103], off nt
	global_store_dwordx4 v[88:89], v[80:83], off nt
	v_lshl_add_u64 v[72:73], v[72:73], 0, v[114:115]
	v_cndmask_b32_e64 v51, v60, v52, s[2:3]
	v_add_co_u32_e32 v80, vcc, s54, v88
	v_mov_b32_e32 v58, v137
	v_mov_b32_dpp v59, v50 row_ror:8 row_mask:0xf bank_mask:0xf
	v_mov_b32_dpp v63, v48 row_ror:8 row_mask:0xf bank_mask:0xf
	v_cndmask_b32_e64 v50, v62, v56, s[2:3]
	v_add_u32_e32 v56, s0, v152
	v_cvt_pk_bf16_f32 v44, v44, v45
	v_cvt_pk_bf16_f32 v45, v46, v47
	v_cvt_pk_bf16_f32 v41, v42, v43
	v_cvt_pk_bf16_f32 v39, v34, v35
	v_cndmask_b32_e64 v33, v40, v38, s[2:3]
	v_mov_b32_e32 v46, v137
	v_cndmask_b32_e64 v87, v87, v95, s[2:3]
	v_cndmask_b32_e64 v86, v86, v94, s[2:3]
	v_cndmask_b32_e64 v85, v85, v91, s[2:3]
	v_cndmask_b32_e64 v84, v84, v90, s[2:3]
	v_addc_co_u32_e32 v81, vcc, 0, v89, vcc
	v_cndmask_b32_e64 v65, v75, v77, s[2:3]
	v_cndmask_b32_e64 v64, v74, v76, s[2:3]
	v_lshl_add_u64 v[72:73], v[72:73], 0, v[136:137]
	v_mov_b32_dpp v58, v51 row_ror:8 row_mask:0xf bank_mask:0xf
	v_cndmask_b32_e64 v51, v63, v57, s[2:3]
	v_mad_i64_i32 v[56:57], s[20:21], v56, s53, v[112:113]
	v_cndmask_b32_e64 v32, v41, v39, s[2:3]
	v_cndmask_b32_e64 v34, v45, v37, s[2:3]
	v_mov_b32_e32 v43, v137
	v_mov_b32_dpp v46, v33 row_ror:8 row_mask:0xf bank_mask:0xf
	v_mov_b32_e32 v47, v137
	v_cvt_pk_bf16_f32 v24, v24, v25
	v_cvt_pk_bf16_f32 v20, v20, v21
	v_cvt_pk_bf16_f32 v21, v22, v23
	v_cvt_pk_bf16_f32 v22, v16, v17
	global_store_dwordx4 v[80:81], v[84:87], off nt
	global_store_dwordx4 v[72:73], v[64:67], off nt
	v_lshl_add_u64 v[56:57], v[56:57], 0, v[114:115]
	v_cndmask_b32_e64 v35, v44, v36, s[2:3]
	v_add_co_u32_e32 v64, vcc, s54, v72
	v_mov_b32_e32 v42, v137
; __device__ __forceinline__ unsigned cvt_pk_bf16(float lo, float hi) { const cvt_f32x2_t v = {lo, hi}; const cvt_bf16x2_t b = __builtin_convertvector(v, cvt_bf16x2_t); return __builtin_bit_cast(unsigned, b); }
; __device__ __forceinline__ unsigned swap8(unsigned v) { return (unsigned)__builtin_amdgcn_update_dpp(0, (int)v, 0x128  , 0xF, 0xF, false); }
; __device__ __forceinline__ void wide_store(bf16_t* O, int ldc, int rowg  , int col0  , int fr, u32x4 w0, u32x4 w1) {
;     const bool lo = fr < 8;
;     u32x4 snd = lo ? w1 : w0, rcv;
;     rcv.x = swap8(snd.x); rcv.y = swap8(snd.y); rcv.z = swap8(snd.z); rcv.w = swap8(snd.w);
;     const u32x4 first = lo ? w0 : rcv, second = lo ? rcv : w1;
;     bf16_t* p = O + (size_t)(rowg + (fr & 7)) * ldc + col0 + (lo ? 0 : 32);
;     __builtin_nontemporal_store(first, (u32x4*)p); __builtin_nontemporal_store(second, (u32x4*)(p + (size_t)8 * ldc));
; }
;     __device__ __forceinline__ void operator()(const f32x4 (&acc)[2][2][4][2], const Unit& u, int wr, int wc, int fr, int fq) const {
;         const int col0 = u.pn * BM + wc * 64 + 8 * fq;
; #pragma unroll
;         for (int ai = 0; ai < 2; ++ai)
; #pragma unroll
;             for (int m = 0; m < 4; ++m) { const int rowg = u.pm * BM + ai * HALF + wr * 64 + m * 16;
;                 const float sc = slots ? rstd_from_slots(slots, rowg + fr, fq) : 1.0f;
;                 u32x4 w[2];
; #pragma unroll
;                 for (int bj = 0; bj < 2; ++bj) { const f32x4 v0 = acc[ai][bj][m][0] * sc, v1 = acc[ai][bj][m][1] * sc;
;                     w[bj].x = cvt_pk_bf16(v0[0], v0[1]); w[bj].y = cvt_pk_bf16(v0[2], v0[3]); w[bj].z = cvt_pk_bf16(v1[0], v1[1]); w[bj].w = cvt_pk_bf16(v1[2], v1[3]); }
;                 wide_store(O, ldc, rowg, col0, fr, w[0], w[1]); }
; template <class Epi, class Sched, bool ALIGN_EPI = false, bool SP2 = false>
; __device__ __forceinline__ void gemm_phase(PG8_LAS unsigned char* lds, const Gemm g, const Sched& S, const Epi& E) {
;     ...
;         if (!has_next) break;
; #pragma unroll
;         for (int a = 0; a < 2; ++a)
; #pragma unroll
;             for (int b = 0; b < 2; ++b)
; #pragma unroll
;                 for (int m = 0; m < 4; ++m)
; #pragma unroll
;                     for (int n = 0; n < 2; ++n) acc[a][b][m][n] = (f32x4){0.f, 0.f, 0.f, 0.f};
;         cur = nxt; cA = nA; cB = nB; ++ui;
;         if constexpr (ALIGN_EPI) { if (wr == 1) PG8_BAR; }
	v_mov_b32_dpp v43, v34 row_ror:8 row_mask:0xf bank_mask:0xf
	v_mov_b32_dpp v47, v32 row_ror:8 row_mask:0xf bank_mask:0xf
	v_cndmask_b32_e64 v34, v46, v40, s[2:3]
	v_add_u32_e32 v40, s0, v155
	v_cvt_pk_bf16_f32 v28, v28, v29
	v_cvt_pk_bf16_f32 v29, v30, v31
	v_cvt_pk_bf16_f32 v25, v26, v27
	v_cvt_pk_bf16_f32 v23, v18, v19
	v_cndmask_b32_e64 v17, v24, v22, s[2:3]
	v_mov_b32_e32 v30, v137
	v_cndmask_b32_e64 v71, v71, v79, s[2:3]
	v_cndmask_b32_e64 v70, v70, v78, s[2:3]
	v_cndmask_b32_e64 v69, v69, v75, s[2:3]
	v_cndmask_b32_e64 v68, v68, v74, s[2:3]
	v_addc_co_u32_e32 v65, vcc, 0, v73, vcc
	v_cndmask_b32_e64 v49, v59, v61, s[2:3]
	v_cndmask_b32_e64 v48, v58, v60, s[2:3]
	v_lshl_add_u64 v[56:57], v[56:57], 0, v[136:137]
	v_mov_b32_dpp v42, v35 row_ror:8 row_mask:0xf bank_mask:0xf
	v_cndmask_b32_e64 v35, v47, v41, s[2:3]
	v_mad_i64_i32 v[40:41], s[20:21], v40, s53, v[112:113]
	v_cndmask_b32_e64 v16, v25, v23, s[2:3]
	v_cndmask_b32_e64 v18, v29, v21, s[2:3]
	v_mov_b32_e32 v27, v137
	v_mov_b32_dpp v30, v17 row_ror:8 row_mask:0xf bank_mask:0xf
	v_mov_b32_e32 v31, v137
	v_cvt_pk_bf16_f32 v8, v8, v9
	v_cvt_pk_bf16_f32 v4, v4, v5
	v_cvt_pk_bf16_f32 v5, v6, v7
	v_cvt_pk_bf16_f32 v6, v0, v1
	global_store_dwordx4 v[64:65], v[68:71], off nt
	global_store_dwordx4 v[56:57], v[48:51], off nt
	v_lshl_add_u64 v[40:41], v[40:41], 0, v[114:115]
	v_cndmask_b32_e64 v19, v28, v20, s[2:3]
	v_add_co_u32_e32 v48, vcc, s54, v56
	v_mov_b32_e32 v26, v137
	v_mov_b32_dpp v27, v18 row_ror:8 row_mask:0xf bank_mask:0xf
	v_mov_b32_dpp v31, v16 row_ror:8 row_mask:0xf bank_mask:0xf
	v_cndmask_b32_e64 v18, v30, v24, s[2:3]
	v_add_u32_e32 v24, s0, v156
	v_cvt_pk_bf16_f32 v12, v12, v13
	v_cvt_pk_bf16_f32 v13, v14, v15
	v_cvt_pk_bf16_f32 v9, v10, v11
	v_cvt_pk_bf16_f32 v7, v2, v3
	v_cndmask_b32_e64 v1, v8, v6, s[2:3]
	v_mov_b32_e32 v14, v137
	v_cndmask_b32_e64 v55, v55, v63, s[2:3]
	v_cndmask_b32_e64 v54, v54, v62, s[2:3]
	v_cndmask_b32_e64 v53, v53, v59, s[2:3]
	v_cndmask_b32_e64 v52, v52, v58, s[2:3]
	v_addc_co_u32_e32 v49, vcc, 0, v57, vcc
	v_cndmask_b32_e64 v33, v43, v45, s[2:3]
	v_cndmask_b32_e64 v32, v42, v44, s[2:3]
	v_lshl_add_u64 v[40:41], v[40:41], 0, v[136:137]
	v_mov_b32_dpp v26, v19 row_ror:8 row_mask:0xf bank_mask:0xf
	v_cndmask_b32_e64 v19, v31, v25, s[2:3]
	v_mad_i64_i32 v[24:25], s[20:21], v24, s53, v[112:113]
	v_cndmask_b32_e64 v0, v9, v7, s[2:3]
	v_cndmask_b32_e64 v2, v13, v5, s[2:3]
	v_mov_b32_e32 v11, v137
	v_mov_b32_dpp v14, v1 row_ror:8 row_mask:0xf bank_mask:0xf
	v_mov_b32_e32 v15, v137
	global_store_dwordx4 v[48:49], v[52:55], off nt
	global_store_dwordx4 v[40:41], v[32:35], off nt
	v_lshl_add_u64 v[24:25], v[24:25], 0, v[114:115]
	v_cndmask_b32_e64 v3, v12, v4, s[2:3]
	v_add_co_u32_e32 v32, vcc, s54, v40
	v_mov_b32_e32 v10, v137
	v_mov_b32_dpp v11, v2 row_ror:8 row_mask:0xf bank_mask:0xf
	v_mov_b32_dpp v15, v0 row_ror:8 row_mask:0xf bank_mask:0xf
	v_cndmask_b32_e64 v2, v14, v8, s[2:3]
	v_add_u32_e32 v8, s0, v157
	v_cndmask_b32_e64 v39, v39, v47, s[2:3]
	v_cndmask_b32_e64 v38, v38, v46, s[2:3]
	v_cndmask_b32_e64 v37, v37, v43, s[2:3]
	v_cndmask_b32_e64 v36, v36, v42, s[2:3]
	v_addc_co_u32_e32 v33, vcc, 0, v41, vcc
	v_cndmask_b32_e64 v17, v27, v29, s[2:3]
	v_cndmask_b32_e64 v16, v26, v28, s[2:3]
	v_lshl_add_u64 v[24:25], v[24:25], 0, v[136:137]
	v_mov_b32_dpp v10, v3 row_ror:8 row_mask:0xf bank_mask:0xf
	v_cndmask_b32_e64 v3, v15, v9, s[2:3]
	v_mad_i64_i32 v[8:9], s[0:1], v8, s53, v[112:113]
	global_store_dwordx4 v[32:33], v[36:39], off nt
	global_store_dwordx4 v[24:25], v[16:19], off nt
	v_lshl_add_u64 v[8:9], v[8:9], 0, v[114:115]
	v_cndmask_b32_e64 v23, v23, v31, s[2:3]
	v_add_co_u32_e32 v16, vcc, s54, v24
	v_cndmask_b32_e64 v22, v22, v30, s[2:3]
	v_cndmask_b32_e64 v21, v21, v27, s[2:3]
	v_cndmask_b32_e64 v20, v20, v26, s[2:3]
	v_addc_co_u32_e32 v17, vcc, 0, v25, vcc
	v_cndmask_b32_e64 v1, v11, v13, s[2:3]
	v_cndmask_b32_e64 v0, v10, v12, s[2:3]
	v_lshl_add_u64 v[8:9], v[8:9], 0, v[136:137]
	global_store_dwordx4 v[16:17], v[20:23], off nt
	global_store_dwordx4 v[8:9], v[0:3], off nt
	v_cndmask_b32_e64 v7, v7, v15, s[2:3]
	v_cndmask_b32_e64 v6, v6, v14, s[2:3]
	v_add_co_u32_e32 v0, vcc, 0x24000, v8
	v_cndmask_b32_e64 v5, v5, v11, s[2:3]
	s_nop 0
	v_addc_co_u32_e32 v1, vcc, 0, v9, vcc
	v_cndmask_b32_e64 v4, v4, v10, s[2:3]
	s_andn2_b64 vcc, exec, s[4:5]
	s_mov_b64 s[0:1], -1
	global_store_dwordx4 v[0:1], v[4:7], off nt
	s_cbranch_vccnz .LBB0_211
	s_andn2_b64 vcc, exec, s[8:9]
	s_cbranch_vccnz .LBB0_210
	s_branch .LBB0_210

; #define PG8_STAGE(bufoff, gbase, voff) do { _Pragma("unroll") for (int _i = 0; _i < 2; ++_i) \
;         __builtin_amdgcn_global_load_lds((const unsigned*)((const char*)(gbase) + (voff)[_i]), (PG8_LAS unsigned*)(lds + (bufoff) + ldsw + _i * 8192), 16, 0, PG8_LOAD_AUX); } while (0)
; #define PG8_LDA(dst, b, h) do { _Pragma("unroll") for (int m = 0; m < 4; ++m) _Pragma("unroll") for (int k = 0; k < 2; ++k) dst[m][k] = *(const PG8_LAS bf16x8*)(lds + PG8_SA(b, h) + aoff + m * 2048 + k * 1024); } while (0)
; #define PG8_LDB(dst, b, h) do { _Pragma("unroll") for (int n = 0; n < 2; ++n) _Pragma("unroll") for (int k = 0; k < 2; ++k) dst[n][k] = *(const PG8_LAS bf16x8*)(lds + PG8_SB(b, h) + boff + n * 2048 + k * 1024); } while (0)
; #define PG8_MMA(ai, bj, At, Bt) do { __builtin_amdgcn_s_setprio(1); _Pragma("unroll") for (int m = 0; m < 4; ++m) _Pragma("unroll") for (int n = 0; n < 2; ++n) _Pragma("unroll") for (int k = 0; k < 2; ++k) \
;         acc[ai][bj][m][n] = __builtin_amdgcn_mfma_f32_16x16x32_bf16(Bt[n][k], At[m][k], acc[ai][bj][m][n], 0, 0, 0); __builtin_amdgcn_s_setprio(0); } while (0)
; #define PG8_WAIT_V(n) asm volatile("s_waitcnt vmcnt(" #n ")" ::: "memory")
; #define PG8_WAIT_L(n) asm volatile("s_waitcnt lgkmcnt(" #n ")" ::: "memory")
; #define PG8_BAR __builtin_amdgcn_s_barrier()
; #define PG8_SCHED __builtin_amdgcn_sched_barrier(0)
; template <class Epi, class Sched, bool ALIGN_EPI = false, bool SP2 = false>
; __device__ __forceinline__ void gemm_phase(PG8_LAS unsigned char* lds, const Gemm g, const Sched& S, const Epi& E) {
;     ...
;             PG8_LDB(B0, 1, 0); PG8_LDB(B1, 1, 1); PG8_SCHED; PG8_LDA(At, 1, 0); PG8_STAGE(PG8_SA(0, 1), a2 + hstepA, voffA);
;             PG8_WAIT_V(8); PG8_WAIT_L(0); PG8_BAR; PG8_MMA(0, 0, At, B0); PG8_MMA(0, 1, At, B1); PG8_BAR; PG8_SCHED;
;             PG8_LDA(At, 1, 1); PG8_STAGE(PG8_SB(1, 0), b3, voffB); PG8_STAGE(PG8_SB(1, 1), b3 + hstepB, voffB); PG8_STAGE(PG8_SA(1, 0), a3, voffA);
;             PG8_WAIT_V(8); PG8_WAIT_L(0); PG8_BAR; PG8_MMA(1, 0, At, B0); PG8_MMA(1, 1, At, B1); PG8_BAR; PG8_SCHED;
.Lkmid_P3:
	s_add_i32 s29, 0, 0x18000
	s_add_i32 s38, 0, 0x1c000
	v_add_u32_e32 v174, s29, v146
	v_add_u32_e32 v190, s38, v146
	ds_read_b128 v[162:165], v174
	ds_read_b128 v[166:169], v174 offset:1024
	ds_read_b128 v[170:173], v174 offset:2048
	ds_read_b128 v[174:177], v174 offset:3072
	ds_read_b128 v[178:181], v190
	ds_read_b128 v[182:185], v190 offset:1024
	ds_read_b128 v[186:189], v190 offset:2048
	ds_read_b128 v[190:193], v190 offset:3072
	s_add_u32 s30, s34, 0x40000
	s_addc_u32 s31, s35, 0
	s_mov_b32 m0, s46
	v_lshl_add_u64 v[234:235], s[30:31], 0, v[134:135]
	ds_read_b128 v[194:197], v161 offset:32768
	ds_read_b128 v[198:201], v161 offset:33792
	ds_read_b128 v[202:205], v161 offset:34816
	ds_read_b128 v[206:209], v161 offset:35840
	ds_read_b128 v[210:213], v161 offset:36864
	ds_read_b128 v[214:217], v161 offset:37888
	ds_read_b128 v[218:221], v161 offset:38912
	ds_read_b128 v[222:225], v161 offset:39936
	global_load_lds_dwordx4 v[234:235], off
	v_lshl_add_u64 v[234:235], s[30:31], 0, v[130:131]
	s_mov_b32 m0, s47
	s_nop 0
	global_load_lds_dwordx4 v[234:235], off
	s_waitcnt vmcnt(8)
	s_waitcnt lgkmcnt(0)
	s_barrier
	s_waitcnt lgkmcnt(0)
	v_mfma_f32_16x16x32_bf16 v[124:127], v[162:165], v[194:197], v[124:127]
	v_mfma_f32_16x16x32_bf16 v[120:123], v[170:173], v[194:197], v[120:123]
	v_mfma_f32_16x16x32_bf16 v[108:111], v[162:165], v[202:205], v[108:111]
	v_mfma_f32_16x16x32_bf16 v[104:107], v[170:173], v[202:205], v[104:107]
	v_mfma_f32_16x16x32_bf16 v[92:95], v[162:165], v[210:213], v[92:95]
	v_mfma_f32_16x16x32_bf16 v[88:91], v[170:173], v[210:213], v[88:91]
	v_mfma_f32_16x16x32_bf16 v[76:79], v[162:165], v[218:221], v[76:79]
	v_mfma_f32_16x16x32_bf16 v[72:75], v[170:173], v[218:221], v[72:75]
	v_mfma_f32_16x16x32_bf16 v[124:127], v[166:169], v[198:201], v[124:127]
	v_mfma_f32_16x16x32_bf16 v[120:123], v[174:177], v[198:201], v[120:123]
	v_mfma_f32_16x16x32_bf16 v[108:111], v[166:169], v[206:209], v[108:111]
	v_mfma_f32_16x16x32_bf16 v[104:107], v[174:177], v[206:209], v[104:107]
	v_mfma_f32_16x16x32_bf16 v[92:95], v[166:169], v[214:217], v[92:95]
	v_mfma_f32_16x16x32_bf16 v[88:91], v[174:177], v[214:217], v[88:91]
	v_mfma_f32_16x16x32_bf16 v[76:79], v[166:169], v[222:225], v[76:79]
	v_mfma_f32_16x16x32_bf16 v[72:75], v[174:177], v[222:225], v[72:75]
	v_mfma_f32_16x16x32_bf16 v[116:119], v[178:181], v[194:197], v[116:119]
	v_mfma_f32_16x16x32_bf16 v[112:115], v[186:189], v[194:197], v[112:115]
	v_mfma_f32_16x16x32_bf16 v[100:103], v[178:181], v[202:205], v[100:103]
	v_mfma_f32_16x16x32_bf16 v[96:99], v[186:189], v[202:205], v[96:99]
	v_mfma_f32_16x16x32_bf16 v[84:87], v[178:181], v[210:213], v[84:87]
	v_mfma_f32_16x16x32_bf16 v[80:83], v[186:189], v[210:213], v[80:83]
	v_mfma_f32_16x16x32_bf16 v[68:71], v[178:181], v[218:221], v[68:71]
	v_mfma_f32_16x16x32_bf16 v[64:67], v[186:189], v[218:221], v[64:67]
	v_mfma_f32_16x16x32_bf16 v[116:119], v[182:185], v[198:201], v[116:119]
	v_mfma_f32_16x16x32_bf16 v[112:115], v[190:193], v[198:201], v[112:115]
	v_mfma_f32_16x16x32_bf16 v[100:103], v[182:185], v[206:209], v[100:103]
	v_mfma_f32_16x16x32_bf16 v[96:99], v[190:193], v[206:209], v[96:99]
	v_mfma_f32_16x16x32_bf16 v[84:87], v[182:185], v[214:217], v[84:87]
	v_mfma_f32_16x16x32_bf16 v[80:83], v[190:193], v[214:217], v[80:83]
	v_mfma_f32_16x16x32_bf16 v[68:71], v[182:185], v[222:225], v[68:71]
	v_mfma_f32_16x16x32_bf16 v[64:67], v[190:193], v[222:225], v[64:67]
	s_barrier
	s_add_i32 s29, s29, s37
	v_lshl_add_u64 v[226:227], v[226:227], 0, s[10:11]
	s_mov_b32 m0, s29
	ds_read_b128 v[194:197], v161 offset:49152
	ds_read_b128 v[198:201], v161 offset:50176
	ds_read_b128 v[202:205], v161 offset:51200
	ds_read_b128 v[206:209], v161 offset:52224
	ds_read_b128 v[210:213], v161 offset:53248
	ds_read_b128 v[214:217], v161 offset:54272
	ds_read_b128 v[218:221], v161 offset:55296
	ds_read_b128 v[222:225], v161 offset:56320
	global_load_lds_dwordx4 v[226:227], off
	s_add_i32 m0, s29, 0x2000
	s_add_u32 s22, s22, 0x10080
	v_lshl_add_u64 v[226:227], v[228:229], 0, s[10:11]
	s_addc_u32 s23, s23, 0
	s_add_i32 s29, s38, s37
	global_load_lds_dwordx4 v[226:227], off
	v_lshl_add_u64 v[226:227], s[22:23], 0, v[132:133]
	s_mov_b32 m0, s29
	s_nop 0
	global_load_lds_dwordx4 v[226:227], off
	v_lshl_add_u64 v[226:227], s[22:23], 0, v[128:129]
	s_add_i32 m0, s29, 0x2000
	s_nop 0
	global_load_lds_dwordx4 v[226:227], off
	v_lshl_add_u64 v[226:227], v[230:231], 0, s[10:11]
	s_mov_b32 m0, s49
	s_nop 0
	global_load_lds_dwordx4 v[226:227], off
	v_lshl_add_u64 v[226:227], v[232:233], 0, s[10:11]
	s_mov_b32 m0, s50
	s_nop 0
	global_load_lds_dwordx4 v[226:227], off
	s_waitcnt vmcnt(8)
	s_waitcnt lgkmcnt(0)
	s_barrier
; __device__ __forceinline__ unsigned cvt_pk_bf16(float lo, float hi) { const cvt_f32x2_t v = {lo, hi}; const cvt_bf16x2_t b = __builtin_convertvector(v, cvt_bf16x2_t); return __builtin_bit_cast(unsigned, b); }
; #define PG8_STAGE(bufoff, gbase, voff) do { _Pragma("unroll") for (int _i = 0; _i < 2; ++_i) \
;         __builtin_amdgcn_global_load_lds((const unsigned*)((const char*)(gbase) + (voff)[_i]), (PG8_LAS unsigned*)(lds + (bufoff) + ldsw + _i * 8192), 16, 0, PG8_LOAD_AUX); } while (0)
; #define PG8_LDA(dst, b, h) do { _Pragma("unroll") for (int m = 0; m < 4; ++m) _Pragma("unroll") for (int k = 0; k < 2; ++k) dst[m][k] = *(const PG8_LAS bf16x8*)(lds + PG8_SA(b, h) + aoff + m * 2048 + k * 1024); } while (0)
; #define PG8_WAIT_V(n) asm volatile("s_waitcnt vmcnt(" #n ")" ::: "memory")
; #define PG8_WAIT_L(n) asm volatile("s_waitcnt lgkmcnt(" #n ")" ::: "memory")
; #define PG8_BAR __builtin_amdgcn_s_barrier()
;     __device__ __forceinline__ void operator()(const f32x4 (&acc)[2][2][4][2], const Unit& u, int wr, int wc, int fr, int fq) const {
;         const int col0 = u.pn * BM + wc * 64 + 8 * fq;
; #pragma unroll
;         for (int ai = 0; ai < 2; ++ai)
; #pragma unroll
;             for (int m = 0; m < 4; ++m) { const int rowg = u.pm * BM + ai * HALF + wr * 64 + m * 16;
;                 const float sc = slots ? rstd_from_slots(slots, rowg + fr, fq) : 1.0f;
;                 u32x4 w[2];
; #pragma unroll
;                 for (int bj = 0; bj < 2; ++bj) { const f32x4 v0 = acc[ai][bj][m][0] * sc, v1 = acc[ai][bj][m][1] * sc;
;                     w[bj].x = cvt_pk_bf16(v0[0], v0[1]); w[bj].y = cvt_pk_bf16(v0[2], v0[3]); w[bj].z = cvt_pk_bf16(v1[0], v1[1]); w[bj].w = cvt_pk_bf16(v1[2], v1[3]); }
;                 wide_store(O, ldc, rowg, col0, fr, w[0], w[1]); }
; template <class Epi, class Sched, bool ALIGN_EPI = false, bool SP2 = false>
; __device__ __forceinline__ void gemm_phase(PG8_LAS unsigned char* lds, const Gemm g, const Sched& S, const Epi& E) {
;     ...
;             PG8_WAIT_V(8); PG8_WAIT_L(0); PG8_BAR; PG8_MMA(0, 0, At, B0); PG8_MMA(0, 1, At, B1); PG8_BAR; PG8_SCHED;
;             PG8_LDA(At, 1, 1); PG8_STAGE(PG8_SB(1, 0), b3, voffB); PG8_STAGE(PG8_SB(1, 1), b3 + hstepB, voffB); PG8_STAGE(PG8_SA(1, 0), a3, voffA);
;             PG8_WAIT_V(8); PG8_WAIT_L(0); PG8_BAR; PG8_MMA(1, 0, At, B0); PG8_MMA(1, 1, At, B1); PG8_BAR; PG8_SCHED;
	s_waitcnt lgkmcnt(0)
	v_mfma_f32_16x16x32_bf16 v[60:63], v[162:165], v[194:197], v[60:63]
	v_mfma_f32_16x16x32_bf16 v[56:59], v[170:173], v[194:197], v[56:59]
	v_mfma_f32_16x16x32_bf16 v[44:47], v[162:165], v[202:205], v[44:47]
	v_mfma_f32_16x16x32_bf16 v[40:43], v[170:173], v[202:205], v[40:43]
	v_mfma_f32_16x16x32_bf16 v[28:31], v[162:165], v[210:213], v[28:31]
	v_mfma_f32_16x16x32_bf16 v[24:27], v[170:173], v[210:213], v[24:27]
	v_mfma_f32_16x16x32_bf16 v[12:15], v[162:165], v[218:221], v[12:15]
	v_mfma_f32_16x16x32_bf16 v[8:11], v[170:173], v[218:221], v[8:11]
	v_mfma_f32_16x16x32_bf16 v[60:63], v[166:169], v[198:201], v[60:63]
	v_mfma_f32_16x16x32_bf16 v[56:59], v[174:177], v[198:201], v[56:59]
	v_mfma_f32_16x16x32_bf16 v[44:47], v[166:169], v[206:209], v[44:47]
	v_mfma_f32_16x16x32_bf16 v[40:43], v[174:177], v[206:209], v[40:43]
	v_mfma_f32_16x16x32_bf16 v[28:31], v[166:169], v[214:217], v[28:31]
	v_mfma_f32_16x16x32_bf16 v[24:27], v[174:177], v[214:217], v[24:27]
	v_mfma_f32_16x16x32_bf16 v[12:15], v[166:169], v[222:225], v[12:15]
	v_mfma_f32_16x16x32_bf16 v[8:11], v[174:177], v[222:225], v[8:11]
	v_mfma_f32_16x16x32_bf16 v[52:55], v[178:181], v[194:197], v[52:55]
	v_mfma_f32_16x16x32_bf16 v[48:51], v[186:189], v[194:197], v[48:51]
	v_mfma_f32_16x16x32_bf16 v[36:39], v[178:181], v[202:205], v[36:39]
	v_mfma_f32_16x16x32_bf16 v[32:35], v[186:189], v[202:205], v[32:35]
	v_mfma_f32_16x16x32_bf16 v[20:23], v[178:181], v[210:213], v[20:23]
	v_mfma_f32_16x16x32_bf16 v[16:19], v[186:189], v[210:213], v[16:19]
	v_mfma_f32_16x16x32_bf16 v[4:7], v[178:181], v[218:221], v[4:7]
	v_mfma_f32_16x16x32_bf16 v[0:3], v[186:189], v[218:221], v[0:3]
	v_mfma_f32_16x16x32_bf16 v[52:55], v[182:185], v[198:201], v[52:55]
	v_mfma_f32_16x16x32_bf16 v[48:51], v[190:193], v[198:201], v[48:51]
	v_mfma_f32_16x16x32_bf16 v[36:39], v[182:185], v[206:209], v[36:39]
	v_mfma_f32_16x16x32_bf16 v[32:35], v[190:193], v[206:209], v[32:35]
	v_mfma_f32_16x16x32_bf16 v[20:23], v[182:185], v[214:217], v[20:23]
	v_mfma_f32_16x16x32_bf16 v[16:19], v[190:193], v[214:217], v[16:19]
	v_mfma_f32_16x16x32_bf16 v[4:7], v[182:185], v[222:225], v[4:7]
	v_mfma_f32_16x16x32_bf16 v[0:3], v[190:193], v[222:225], v[0:3]
	s_barrier
	s_add_i32 s28, s28, 2
	s_add_u32 s20, s20, 0x100
	s_addc_u32 s21, s21, 0
	s_add_u32 s26, s26, 0x100
	s_addc_u32 s27, s27, 0
	s_cmp_gt_u32 s28, 13
	s_cbranch_scc0 .LBB0_369
	s_andn2_b64 vcc, s[12:13], s[4:5]
	s_cbranch_vccz .LBB0_372
	s_barrier
.LBB0_372:
	v_cvt_pk_bf16_f32 v120, v120, v121
	v_cvt_pk_bf16_f32 v112, v112, v113
	v_cvt_pk_bf16_f32 v121, v122, v123
	v_cvt_pk_bf16_f32 v113, v114, v115
	v_cndmask_b32_e64 v115, v120, v112, s[2:3]
	v_mov_b32_e32 v122, 0
	v_cvt_pk_bf16_f32 v124, v124, v125
	v_cvt_pk_bf16_f32 v125, v126, v127
	v_cvt_pk_bf16_f32 v126, v116, v117
	v_cvt_pk_bf16_f32 v127, v118, v119
	v_cndmask_b32_e64 v114, v121, v113, s[2:3]
	v_mov_b32_dpp v122, v115 row_ror:8 row_mask:0xf bank_mask:0xf
	v_mov_b32_e32 v115, 0
	v_readlane_b32 s30, v239, 49
	v_lshl_or_b32 v162, s1, 8, v147
	s_lshl_b32 s0, s0, 8
	v_cndmask_b32_e64 v116, v125, v127, s[2:3]
	v_cndmask_b32_e64 v117, v124, v126, s[2:3]
	v_mov_b32_e32 v164, 0
	v_mov_b32_e32 v165, 0
	v_mov_b32_dpp v115, v114 row_ror:8 row_mask:0xf bank_mask:0xf
	v_readlane_b32 s31, v239, 50
	v_cvt_pk_bf16_f32 v104, v104, v105
	v_cvt_pk_bf16_f32 v100, v100, v101
	v_cvt_pk_bf16_f32 v101, v102, v103
	v_cvt_pk_bf16_f32 v102, v96, v97
	v_ashrrev_i32_e32 v163, 31, v162
	v_mov_b32_dpp v164, v117 row_ror:8 row_mask:0xf bank_mask:0xf
	v_mov_b32_dpp v165, v116 row_ror:8 row_mask:0xf bank_mask:0xf
	v_cndmask_b32_e64 v118, v122, v120, s[2:3]
	v_cndmask_b32_e64 v123, v113, v115, s[2:3]
	v_cndmask_b32_e64 v122, v112, v122, s[2:3]
	v_add_u32_e32 v114, s0, v148
	v_mov_b64_e32 v[112:113], s[30:31]
	v_cvt_pk_bf16_f32 v108, v108, v109
	v_cvt_pk_bf16_f32 v109, v110, v111
	v_cvt_pk_bf16_f32 v105, v106, v107
	v_cvt_pk_bf16_f32 v103, v98, v99
	v_cndmask_b32_e64 v97, v104, v102, s[2:3]
	v_mov_b32_e32 v110, v137
	v_cndmask_b32_e64 v119, v115, v121, s[2:3]
	v_cndmask_b32_e64 v117, v165, v125, s[2:3]
	v_cndmask_b32_e64 v116, v164, v124, s[2:3]
	v_mad_i64_i32 v[124:125], s[20:21], v114, s55, v[112:113]
	v_lshlrev_b64 v[114:115], 1, v[162:163]
	v_cndmask_b32_e64 v96, v105, v103, s[2:3]
	v_cndmask_b32_e64 v98, v109, v101, s[2:3]
	v_mov_b32_e32 v107, v137
	v_mov_b32_dpp v110, v97 row_ror:8 row_mask:0xf bank_mask:0xf
	v_mov_b32_e32 v111, v137
	v_cvt_pk_bf16_f32 v88, v88, v89
	v_cvt_pk_bf16_f32 v84, v84, v85
	v_cvt_pk_bf16_f32 v85, v86, v87
	v_cvt_pk_bf16_f32 v86, v80, v81
	v_lshl_add_u64 v[124:125], v[124:125], 0, v[114:115]
	v_cndmask_b32_e64 v99, v108, v100, s[2:3]
	v_mov_b32_e32 v106, v137
	v_mov_b32_dpp v107, v98 row_ror:8 row_mask:0xf bank_mask:0xf
	v_mov_b32_dpp v111, v96 row_ror:8 row_mask:0xf bank_mask:0xf
	v_cndmask_b32_e64 v98, v110, v104, s[2:3]
	v_add_u32_e32 v104, s0, v149
	v_cvt_pk_bf16_f32 v92, v92, v93
	v_cvt_pk_bf16_f32 v93, v94, v95
	v_cvt_pk_bf16_f32 v89, v90, v91
	v_cvt_pk_bf16_f32 v87, v82, v83
	v_cndmask_b32_e64 v81, v88, v86, s[2:3]
	v_mov_b32_e32 v94, v137
	v_lshl_add_u64 v[124:125], v[124:125], 0, v[136:137]
	v_mov_b32_dpp v106, v99 row_ror:8 row_mask:0xf bank_mask:0xf
	v_cndmask_b32_e64 v99, v111, v105, s[2:3]
	v_mad_i64_i32 v[104:105], s[20:21], v104, s55, v[112:113]
	v_cndmask_b32_e64 v80, v89, v87, s[2:3]
	v_cndmask_b32_e64 v82, v93, v85, s[2:3]
	v_mov_b32_e32 v91, v137
	v_mov_b32_dpp v94, v81 row_ror:8 row_mask:0xf bank_mask:0xf
	v_mov_b32_e32 v95, v137
	v_cvt_pk_bf16_f32 v72, v72, v73
	v_cvt_pk_bf16_f32 v68, v68, v69
	v_cvt_pk_bf16_f32 v69, v70, v71
	v_cvt_pk_bf16_f32 v70, v64, v65
	global_store_dwordx4 v[124:125], v[116:119], off nt
; __device__ __forceinline__ unsigned cvt_pk_bf16(float lo, float hi) { const cvt_f32x2_t v = {lo, hi}; const cvt_bf16x2_t b = __builtin_convertvector(v, cvt_bf16x2_t); return __builtin_bit_cast(unsigned, b); }
; __device__ __forceinline__ unsigned swap8(unsigned v) { return (unsigned)__builtin_amdgcn_update_dpp(0, (int)v, 0x128  , 0xF, 0xF, false); }
; __device__ __forceinline__ void wide_store(bf16_t* O, int ldc, int rowg  , int col0  , int fr, u32x4 w0, u32x4 w1) {
;     const bool lo = fr < 8;
;     u32x4 snd = lo ? w1 : w0, rcv;
;     rcv.x = swap8(snd.x); rcv.y = swap8(snd.y); rcv.z = swap8(snd.z); rcv.w = swap8(snd.w);
;     const u32x4 first = lo ? w0 : rcv, second = lo ? rcv : w1;
;     bf16_t* p = O + (size_t)(rowg + (fr & 7)) * ldc + col0 + (lo ? 0 : 32);
;     __builtin_nontemporal_store(first, (u32x4*)p); __builtin_nontemporal_store(second, (u32x4*)(p + (size_t)8 * ldc));
; }
;     __device__ __forceinline__ void operator()(const f32x4 (&acc)[2][2][4][2], const Unit& u, int wr, int wc, int fr, int fq) const {
;         const int col0 = u.pn * BM + wc * 64 + 8 * fq;
; #pragma unroll
;         for (int ai = 0; ai < 2; ++ai)
; #pragma unroll
;             for (int m = 0; m < 4; ++m) { const int rowg = u.pm * BM + ai * HALF + wr * 64 + m * 16;
;                 const float sc = slots ? rstd_from_slots(slots, rowg + fr, fq) : 1.0f;
;                 u32x4 w[2];
; #pragma unroll
;                 for (int bj = 0; bj < 2; ++bj) { const f32x4 v0 = acc[ai][bj][m][0] * sc, v1 = acc[ai][bj][m][1] * sc;
;                     w[bj].x = cvt_pk_bf16(v0[0], v0[1]); w[bj].y = cvt_pk_bf16(v0[2], v0[3]); w[bj].z = cvt_pk_bf16(v1[0], v1[1]); w[bj].w = cvt_pk_bf16(v1[2], v1[3]); }
;                 wide_store(O, ldc, rowg, col0, fr, w[0], w[1]); }
	v_lshl_add_u64 v[104:105], v[104:105], 0, v[114:115]
	v_cndmask_b32_e64 v83, v92, v84, s[2:3]
	v_add_co_u32_e32 v116, vcc, s56, v124
	v_mov_b32_e32 v90, v137
	v_mov_b32_dpp v91, v82 row_ror:8 row_mask:0xf bank_mask:0xf
	v_mov_b32_dpp v95, v80 row_ror:8 row_mask:0xf bank_mask:0xf
	v_cndmask_b32_e64 v82, v94, v88, s[2:3]
	v_add_u32_e32 v88, s0, v150
	v_cvt_pk_bf16_f32 v76, v76, v77
	v_cvt_pk_bf16_f32 v77, v78, v79
	v_cvt_pk_bf16_f32 v73, v74, v75
	v_cvt_pk_bf16_f32 v71, v66, v67
	v_cndmask_b32_e64 v65, v72, v70, s[2:3]
	v_mov_b32_e32 v78, v137
	v_cndmask_b32_e64 v121, v127, v165, s[2:3]
	v_cndmask_b32_e64 v120, v126, v164, s[2:3]
	v_addc_co_u32_e32 v117, vcc, 0, v125, vcc
	v_cndmask_b32_e64 v97, v107, v109, s[2:3]
	v_cndmask_b32_e64 v96, v106, v108, s[2:3]
	v_lshl_add_u64 v[104:105], v[104:105], 0, v[136:137]
	v_mov_b32_dpp v90, v83 row_ror:8 row_mask:0xf bank_mask:0xf
	v_cndmask_b32_e64 v83, v95, v89, s[2:3]
	v_mad_i64_i32 v[88:89], s[20:21], v88, s55, v[112:113]
	v_cndmask_b32_e64 v64, v73, v71, s[2:3]
	v_cndmask_b32_e64 v66, v77, v69, s[2:3]
	v_mov_b32_e32 v75, v137
	v_mov_b32_dpp v78, v65 row_ror:8 row_mask:0xf bank_mask:0xf
	v_mov_b32_e32 v79, v137
	v_cvt_pk_bf16_f32 v56, v56, v57
	v_cvt_pk_bf16_f32 v52, v52, v53
	v_cvt_pk_bf16_f32 v53, v54, v55
	v_cvt_pk_bf16_f32 v54, v48, v49
	global_store_dwordx4 v[116:117], v[120:123], off nt
	global_store_dwordx4 v[104:105], v[96:99], off nt
	v_lshl_add_u64 v[88:89], v[88:89], 0, v[114:115]
	v_cndmask_b32_e64 v67, v76, v68, s[2:3]
	v_add_co_u32_e32 v96, vcc, s56, v104
	v_mov_b32_e32 v74, v137
	v_mov_b32_dpp v75, v66 row_ror:8 row_mask:0xf bank_mask:0xf
	v_mov_b32_dpp v79, v64 row_ror:8 row_mask:0xf bank_mask:0xf
	v_cndmask_b32_e64 v66, v78, v72, s[2:3]
	v_add_u32_e32 v72, s0, v151
	v_cvt_pk_bf16_f32 v60, v60, v61
	v_cvt_pk_bf16_f32 v61, v62, v63
	v_cvt_pk_bf16_f32 v57, v58, v59
	v_cvt_pk_bf16_f32 v55, v50, v51
	v_cndmask_b32_e64 v49, v56, v54, s[2:3]
	v_mov_b32_e32 v62, v137
	v_cndmask_b32_e64 v103, v103, v111, s[2:3]
	v_cndmask_b32_e64 v102, v102, v110, s[2:3]
	v_cndmask_b32_e64 v101, v101, v107, s[2:3]
	v_cndmask_b32_e64 v100, v100, v106, s[2:3]
	v_addc_co_u32_e32 v97, vcc, 0, v105, vcc
	v_cndmask_b32_e64 v81, v91, v93, s[2:3]
	v_cndmask_b32_e64 v80, v90, v92, s[2:3]
	v_lshl_add_u64 v[88:89], v[88:89], 0, v[136:137]
	v_mov_b32_dpp v74, v67 row_ror:8 row_mask:0xf bank_mask:0xf
	v_cndmask_b32_e64 v67, v79, v73, s[2:3]
	v_mad_i64_i32 v[72:73], s[20:21], v72, s55, v[112:113]
	v_cndmask_b32_e64 v48, v57, v55, s[2:3]
	v_cndmask_b32_e64 v50, v61, v53, s[2:3]
	v_mov_b32_e32 v59, v137
	v_mov_b32_dpp v62, v49 row_ror:8 row_mask:0xf bank_mask:0xf
	v_mov_b32_e32 v63, v137
	v_cvt_pk_bf16_f32 v40, v40, v41
	v_cvt_pk_bf16_f32 v36, v36, v37
	v_cvt_pk_bf16_f32 v37, v38, v39
	v_cvt_pk_bf16_f32 v38, v32, v33
	global_store_dwordx4 v[96:97], v[100:103], off nt
	global_store_dwordx4 v[88:89], v[80:83], off nt
	v_lshl_add_u64 v[72:73], v[72:73], 0, v[114:115]
	v_cndmask_b32_e64 v51, v60, v52, s[2:3]
	v_add_co_u32_e32 v80, vcc, s56, v88
	v_mov_b32_e32 v58, v137
	v_mov_b32_dpp v59, v50 row_ror:8 row_mask:0xf bank_mask:0xf
	v_mov_b32_dpp v63, v48 row_ror:8 row_mask:0xf bank_mask:0xf
	v_cndmask_b32_e64 v50, v62, v56, s[2:3]
	v_add_u32_e32 v56, s0, v152
	v_cvt_pk_bf16_f32 v44, v44, v45
	v_cvt_pk_bf16_f32 v45, v46, v47
	v_cvt_pk_bf16_f32 v41, v42, v43
	v_cvt_pk_bf16_f32 v39, v34, v35
	v_cndmask_b32_e64 v33, v40, v38, s[2:3]
	v_mov_b32_e32 v46, v137
	v_cndmask_b32_e64 v87, v87, v95, s[2:3]
	v_cndmask_b32_e64 v86, v86, v94, s[2:3]
	v_cndmask_b32_e64 v85, v85, v91, s[2:3]
	v_cndmask_b32_e64 v84, v84, v90, s[2:3]
	v_addc_co_u32_e32 v81, vcc, 0, v89, vcc
	v_cndmask_b32_e64 v65, v75, v77, s[2:3]
	v_cndmask_b32_e64 v64, v74, v76, s[2:3]
	v_lshl_add_u64 v[72:73], v[72:73], 0, v[136:137]
	v_mov_b32_dpp v58, v51 row_ror:8 row_mask:0xf bank_mask:0xf
	v_cndmask_b32_e64 v51, v63, v57, s[2:3]
	v_mad_i64_i32 v[56:57], s[20:21], v56, s55, v[112:113]
	v_cndmask_b32_e64 v32, v41, v39, s[2:3]
	v_cndmask_b32_e64 v34, v45, v37, s[2:3]
	v_mov_b32_e32 v43, v137
	v_mov_b32_dpp v46, v33 row_ror:8 row_mask:0xf bank_mask:0xf
	v_mov_b32_e32 v47, v137
	v_cvt_pk_bf16_f32 v24, v24, v25
	v_cvt_pk_bf16_f32 v20, v20, v21
	v_cvt_pk_bf16_f32 v21, v22, v23
	v_cvt_pk_bf16_f32 v22, v16, v17
	global_store_dwordx4 v[80:81], v[84:87], off nt
	global_store_dwordx4 v[72:73], v[64:67], off nt
	v_lshl_add_u64 v[56:57], v[56:57], 0, v[114:115]
	v_cndmask_b32_e64 v35, v44, v36, s[2:3]
	v_add_co_u32_e32 v64, vcc, s56, v72
	v_mov_b32_e32 v42, v137
; __device__ __forceinline__ unsigned cvt_pk_bf16(float lo, float hi) { const cvt_f32x2_t v = {lo, hi}; const cvt_bf16x2_t b = __builtin_convertvector(v, cvt_bf16x2_t); return __builtin_bit_cast(unsigned, b); }
; __device__ __forceinline__ unsigned swap8(unsigned v) { return (unsigned)__builtin_amdgcn_update_dpp(0, (int)v, 0x128  , 0xF, 0xF, false); }
; __device__ __forceinline__ void wide_store(bf16_t* O, int ldc, int rowg  , int col0  , int fr, u32x4 w0, u32x4 w1) {
;     const bool lo = fr < 8;
;     u32x4 snd = lo ? w1 : w0, rcv;
;     rcv.x = swap8(snd.x); rcv.y = swap8(snd.y); rcv.z = swap8(snd.z); rcv.w = swap8(snd.w);
;     const u32x4 first = lo ? w0 : rcv, second = lo ? rcv : w1;
;     bf16_t* p = O + (size_t)(rowg + (fr & 7)) * ldc + col0 + (lo ? 0 : 32);
;     __builtin_nontemporal_store(first, (u32x4*)p); __builtin_nontemporal_store(second, (u32x4*)(p + (size_t)8 * ldc));
; }
;     __device__ __forceinline__ void operator()(const f32x4 (&acc)[2][2][4][2], const Unit& u, int wr, int wc, int fr, int fq) const {
;         const int col0 = u.pn * BM + wc * 64 + 8 * fq;
; #pragma unroll
;         for (int ai = 0; ai < 2; ++ai)
; #pragma unroll
;             for (int m = 0; m < 4; ++m) { const int rowg = u.pm * BM + ai * HALF + wr * 64 + m * 16;
;                 const float sc = slots ? rstd_from_slots(slots, rowg + fr, fq) : 1.0f;
;                 u32x4 w[2];
; #pragma unroll
;                 for (int bj = 0; bj < 2; ++bj) { const f32x4 v0 = acc[ai][bj][m][0] * sc, v1 = acc[ai][bj][m][1] * sc;
;                     w[bj].x = cvt_pk_bf16(v0[0], v0[1]); w[bj].y = cvt_pk_bf16(v0[2], v0[3]); w[bj].z = cvt_pk_bf16(v1[0], v1[1]); w[bj].w = cvt_pk_bf16(v1[2], v1[3]); }
;                 wide_store(O, ldc, rowg, col0, fr, w[0], w[1]); }
; template <class Epi, class Sched, bool ALIGN_EPI = false, bool SP2 = false>
; __device__ __forceinline__ void gemm_phase(PG8_LAS unsigned char* lds, const Gemm g, const Sched& S, const Epi& E) {
;     ...
;         if (!has_next) break;
; #pragma unroll
;         for (int a = 0; a < 2; ++a)
; #pragma unroll
;             for (int b = 0; b < 2; ++b)
; #pragma unroll
;                 for (int m = 0; m < 4; ++m)
; #pragma unroll
;                     for (int n = 0; n < 2; ++n) acc[a][b][m][n] = (f32x4){0.f, 0.f, 0.f, 0.f};
;         cur = nxt; cA = nA; cB = nB; ++ui;
;         if constexpr (ALIGN_EPI) { if (wr == 1) PG8_BAR; }
	v_mov_b32_dpp v43, v34 row_ror:8 row_mask:0xf bank_mask:0xf
	v_mov_b32_dpp v47, v32 row_ror:8 row_mask:0xf bank_mask:0xf
	v_cndmask_b32_e64 v34, v46, v40, s[2:3]
	v_add_u32_e32 v40, s0, v156
	v_cvt_pk_bf16_f32 v28, v28, v29
	v_cvt_pk_bf16_f32 v29, v30, v31
	v_cvt_pk_bf16_f32 v25, v26, v27
	v_cvt_pk_bf16_f32 v23, v18, v19
	v_cndmask_b32_e64 v17, v24, v22, s[2:3]
	v_mov_b32_e32 v30, v137
	v_cndmask_b32_e64 v71, v71, v79, s[2:3]
	v_cndmask_b32_e64 v70, v70, v78, s[2:3]
	v_cndmask_b32_e64 v69, v69, v75, s[2:3]
	v_cndmask_b32_e64 v68, v68, v74, s[2:3]
	v_addc_co_u32_e32 v65, vcc, 0, v73, vcc
	v_cndmask_b32_e64 v49, v59, v61, s[2:3]
	v_cndmask_b32_e64 v48, v58, v60, s[2:3]
	v_lshl_add_u64 v[56:57], v[56:57], 0, v[136:137]
	v_mov_b32_dpp v42, v35 row_ror:8 row_mask:0xf bank_mask:0xf
	v_cndmask_b32_e64 v35, v47, v41, s[2:3]
	v_mad_i64_i32 v[40:41], s[20:21], v40, s55, v[112:113]
	v_cndmask_b32_e64 v16, v25, v23, s[2:3]
	v_cndmask_b32_e64 v18, v29, v21, s[2:3]
	v_mov_b32_e32 v27, v137
	v_mov_b32_dpp v30, v17 row_ror:8 row_mask:0xf bank_mask:0xf
	v_mov_b32_e32 v31, v137
	v_cvt_pk_bf16_f32 v8, v8, v9
	v_cvt_pk_bf16_f32 v4, v4, v5
	v_cvt_pk_bf16_f32 v5, v6, v7
	v_cvt_pk_bf16_f32 v6, v0, v1
	global_store_dwordx4 v[64:65], v[68:71], off nt
	global_store_dwordx4 v[56:57], v[48:51], off nt
	v_lshl_add_u64 v[40:41], v[40:41], 0, v[114:115]
	v_cndmask_b32_e64 v19, v28, v20, s[2:3]
	v_add_co_u32_e32 v48, vcc, s56, v56
	v_mov_b32_e32 v26, v137
	v_mov_b32_dpp v27, v18 row_ror:8 row_mask:0xf bank_mask:0xf
	v_mov_b32_dpp v31, v16 row_ror:8 row_mask:0xf bank_mask:0xf
	v_cndmask_b32_e64 v18, v30, v24, s[2:3]
	v_add_u32_e32 v24, s0, v157
	v_cvt_pk_bf16_f32 v12, v12, v13
	v_cvt_pk_bf16_f32 v13, v14, v15
	v_cvt_pk_bf16_f32 v9, v10, v11
	v_cvt_pk_bf16_f32 v7, v2, v3
	v_cndmask_b32_e64 v1, v8, v6, s[2:3]
	v_mov_b32_e32 v14, v137
	v_cndmask_b32_e64 v55, v55, v63, s[2:3]
	v_cndmask_b32_e64 v54, v54, v62, s[2:3]
	v_cndmask_b32_e64 v53, v53, v59, s[2:3]
	v_cndmask_b32_e64 v52, v52, v58, s[2:3]
	v_addc_co_u32_e32 v49, vcc, 0, v57, vcc
	v_cndmask_b32_e64 v33, v43, v45, s[2:3]
	v_cndmask_b32_e64 v32, v42, v44, s[2:3]
	v_lshl_add_u64 v[40:41], v[40:41], 0, v[136:137]
	v_mov_b32_dpp v26, v19 row_ror:8 row_mask:0xf bank_mask:0xf
	v_cndmask_b32_e64 v19, v31, v25, s[2:3]
	v_mad_i64_i32 v[24:25], s[20:21], v24, s55, v[112:113]
	v_cndmask_b32_e64 v0, v9, v7, s[2:3]
	v_cndmask_b32_e64 v2, v13, v5, s[2:3]
	v_mov_b32_e32 v11, v137
	v_mov_b32_dpp v14, v1 row_ror:8 row_mask:0xf bank_mask:0xf
	v_mov_b32_e32 v15, v137
	global_store_dwordx4 v[48:49], v[52:55], off nt
	global_store_dwordx4 v[40:41], v[32:35], off nt
	v_lshl_add_u64 v[24:25], v[24:25], 0, v[114:115]
	v_cndmask_b32_e64 v3, v12, v4, s[2:3]
	v_add_co_u32_e32 v32, vcc, s56, v40
	v_mov_b32_e32 v10, v137
	v_mov_b32_dpp v11, v2 row_ror:8 row_mask:0xf bank_mask:0xf
	v_mov_b32_dpp v15, v0 row_ror:8 row_mask:0xf bank_mask:0xf
	v_cndmask_b32_e64 v2, v14, v8, s[2:3]
	v_add_u32_e32 v8, s0, v158
	v_cndmask_b32_e64 v39, v39, v47, s[2:3]
	v_cndmask_b32_e64 v38, v38, v46, s[2:3]
	v_cndmask_b32_e64 v37, v37, v43, s[2:3]
	v_cndmask_b32_e64 v36, v36, v42, s[2:3]
	v_addc_co_u32_e32 v33, vcc, 0, v41, vcc
	v_cndmask_b32_e64 v17, v27, v29, s[2:3]
	v_cndmask_b32_e64 v16, v26, v28, s[2:3]
	v_lshl_add_u64 v[24:25], v[24:25], 0, v[136:137]
	v_mov_b32_dpp v10, v3 row_ror:8 row_mask:0xf bank_mask:0xf
	v_cndmask_b32_e64 v3, v15, v9, s[2:3]
	v_mad_i64_i32 v[8:9], s[0:1], v8, s55, v[112:113]
	global_store_dwordx4 v[32:33], v[36:39], off nt
	global_store_dwordx4 v[24:25], v[16:19], off nt
	v_lshl_add_u64 v[8:9], v[8:9], 0, v[114:115]
	v_cndmask_b32_e64 v23, v23, v31, s[2:3]
	v_add_co_u32_e32 v16, vcc, s56, v24
	v_cndmask_b32_e64 v22, v22, v30, s[2:3]
	v_cndmask_b32_e64 v21, v21, v27, s[2:3]
	v_cndmask_b32_e64 v20, v20, v26, s[2:3]
	v_addc_co_u32_e32 v17, vcc, 0, v25, vcc
	v_cndmask_b32_e64 v1, v11, v13, s[2:3]
	v_cndmask_b32_e64 v0, v10, v12, s[2:3]
	v_lshl_add_u64 v[8:9], v[8:9], 0, v[136:137]
	global_store_dwordx4 v[16:17], v[20:23], off nt
	global_store_dwordx4 v[8:9], v[0:3], off nt
	v_cndmask_b32_e64 v7, v7, v15, s[2:3]
	v_cndmask_b32_e64 v6, v6, v14, s[2:3]
	v_add_co_u32_e32 v0, vcc, 0x24000, v8
	v_cndmask_b32_e64 v5, v5, v11, s[2:3]
	s_nop 0
	v_addc_co_u32_e32 v1, vcc, 0, v9, vcc
	v_cndmask_b32_e64 v4, v4, v10, s[2:3]
	s_andn2_b64 vcc, exec, s[4:5]
	s_mov_b64 s[0:1], -1
	global_store_dwordx4 v[0:1], v[4:7], off nt
	s_cbranch_vccnz .LBB0_365
	s_andn2_b64 vcc, exec, s[8:9]
	s_cbranch_vccnz .LBB0_364
	s_branch .LBB0_364
